# GEMM tile headers: accumulators cleared with 64 v_mov_b64 instead of 128 v_mov_b32
# speedup vs baseline: 1.0078x; 1.0078x over previous
.LBB0_184:
	v_mov_b64_e32 v[2:3], 0
	v_mov_b64_e32 v[4:5], 0
	v_mov_b64_e32 v[6:7], 0
	v_mov_b64_e32 v[8:9], 0
	v_mov_b64_e32 v[10:11], 0
	v_mov_b64_e32 v[12:13], 0
	v_mov_b64_e32 v[14:15], 0
	v_mov_b64_e32 v[16:17], 0
	v_mov_b64_e32 v[18:19], 0
	v_mov_b64_e32 v[20:21], 0
	v_mov_b64_e32 v[22:23], 0
	v_mov_b64_e32 v[24:25], 0
	v_mov_b64_e32 v[26:27], 0
	v_mov_b64_e32 v[28:29], 0
	v_mov_b64_e32 v[30:31], 0
	v_mov_b64_e32 v[32:33], 0
	v_mov_b64_e32 v[34:35], 0
	v_mov_b64_e32 v[36:37], 0
	v_mov_b64_e32 v[38:39], 0
	v_mov_b64_e32 v[40:41], 0
	v_mov_b64_e32 v[42:43], 0
	v_mov_b64_e32 v[44:45], 0
	v_mov_b64_e32 v[46:47], 0
	v_mov_b64_e32 v[48:49], 0
	v_mov_b64_e32 v[50:51], 0
	v_mov_b64_e32 v[52:53], 0
	v_mov_b64_e32 v[54:55], 0
	v_mov_b64_e32 v[56:57], 0
	v_mov_b64_e32 v[58:59], 0
	v_mov_b64_e32 v[60:61], 0
	v_mov_b64_e32 v[62:63], 0
	v_mov_b64_e32 v[64:65], 0
	v_mov_b64_e32 v[66:67], 0
	v_mov_b64_e32 v[68:69], 0
	v_mov_b64_e32 v[70:71], 0
	v_mov_b64_e32 v[72:73], 0
	v_mov_b64_e32 v[74:75], 0
	v_mov_b64_e32 v[76:77], 0
	v_mov_b64_e32 v[78:79], 0
	v_mov_b64_e32 v[80:81], 0
	v_mov_b64_e32 v[82:83], 0
	v_mov_b64_e32 v[84:85], 0
	v_mov_b64_e32 v[86:87], 0
	v_mov_b64_e32 v[88:89], 0
	v_mov_b64_e32 v[90:91], 0
	v_mov_b64_e32 v[92:93], 0
	v_mov_b64_e32 v[94:95], 0
	v_mov_b64_e32 v[96:97], 0
	v_mov_b64_e32 v[98:99], 0
	v_mov_b64_e32 v[100:101], 0
	v_mov_b64_e32 v[102:103], 0
	v_mov_b64_e32 v[104:105], 0
	v_mov_b64_e32 v[106:107], 0
	v_mov_b64_e32 v[108:109], 0
	v_mov_b64_e32 v[110:111], 0
	v_mov_b64_e32 v[112:113], 0
	v_mov_b64_e32 v[114:115], 0
	v_mov_b64_e32 v[116:117], 0
	v_mov_b64_e32 v[118:119], 0
	v_mov_b64_e32 v[120:121], 0
	v_mov_b64_e32 v[122:123], 0
	v_mov_b64_e32 v[124:125], 0
	v_mov_b64_e32 v[126:127], 0
	v_mov_b64_e32 v[128:129], 0
	s_mov_b32 s15, 0
	s_mov_b32 s70, 2
	s_movk_i32 s72, 0x2000
	v_readfirstlane_b32 s71, v187
	s_and_b32 s71, s71, 0xc0
	s_lshl_b32 s71, s71, 8
	s_add_u32 s76, s6, 0xfffff000
	s_addc_u32 s77, s7, -1
	s_waitcnt vmcnt(23)
	s_waitcnt vmcnt(22)
	s_waitcnt vmcnt(21)
	s_waitcnt vmcnt(20)
	s_branch .Lg1_loop

.LBB0_1107:
	v_mov_b64_e32 v[2:3], 0
	v_mov_b64_e32 v[4:5], 0
	v_mov_b64_e32 v[6:7], 0
	v_mov_b64_e32 v[8:9], 0
	v_mov_b64_e32 v[10:11], 0
	v_mov_b64_e32 v[12:13], 0
	v_mov_b64_e32 v[14:15], 0
	v_mov_b64_e32 v[16:17], 0
	v_mov_b64_e32 v[18:19], 0
	v_mov_b64_e32 v[20:21], 0
	v_mov_b64_e32 v[22:23], 0
	v_mov_b64_e32 v[24:25], 0
	v_mov_b64_e32 v[26:27], 0
	v_mov_b64_e32 v[28:29], 0
	v_mov_b64_e32 v[30:31], 0
	v_mov_b64_e32 v[32:33], 0
	v_mov_b64_e32 v[34:35], 0
	v_mov_b64_e32 v[36:37], 0
	v_mov_b64_e32 v[38:39], 0
	v_mov_b64_e32 v[40:41], 0
	v_mov_b64_e32 v[42:43], 0
	v_mov_b64_e32 v[44:45], 0
	v_mov_b64_e32 v[46:47], 0
	v_mov_b64_e32 v[48:49], 0
	v_mov_b64_e32 v[50:51], 0
	v_mov_b64_e32 v[52:53], 0
	v_mov_b64_e32 v[54:55], 0
	v_mov_b64_e32 v[56:57], 0
	v_mov_b64_e32 v[58:59], 0
	v_mov_b64_e32 v[60:61], 0
	v_mov_b64_e32 v[62:63], 0
	v_mov_b64_e32 v[64:65], 0
	v_mov_b64_e32 v[66:67], 0
	v_mov_b64_e32 v[68:69], 0
	v_mov_b64_e32 v[70:71], 0
	v_mov_b64_e32 v[72:73], 0
	v_mov_b64_e32 v[74:75], 0
	v_mov_b64_e32 v[76:77], 0
	v_mov_b64_e32 v[78:79], 0
	v_mov_b64_e32 v[80:81], 0
	v_mov_b64_e32 v[82:83], 0
	v_mov_b64_e32 v[84:85], 0
	v_mov_b64_e32 v[86:87], 0
	v_mov_b64_e32 v[88:89], 0
	v_mov_b64_e32 v[90:91], 0
	v_mov_b64_e32 v[92:93], 0
	v_mov_b64_e32 v[94:95], 0
	v_mov_b64_e32 v[96:97], 0
	v_mov_b64_e32 v[98:99], 0
	v_mov_b64_e32 v[100:101], 0
	v_mov_b64_e32 v[102:103], 0
	v_mov_b64_e32 v[104:105], 0
	v_mov_b64_e32 v[106:107], 0
	v_mov_b64_e32 v[108:109], 0
	v_mov_b64_e32 v[110:111], 0
	v_mov_b64_e32 v[112:113], 0
	v_mov_b64_e32 v[114:115], 0
	v_mov_b64_e32 v[116:117], 0
	v_mov_b64_e32 v[118:119], 0
	v_mov_b64_e32 v[120:121], 0
	v_mov_b64_e32 v[122:123], 0
	v_mov_b64_e32 v[124:125], 0
	v_mov_b64_e32 v[126:127], 0
	v_mov_b64_e32 v[128:129], 0
	s_mov_b32 s39, 0
	s_mov_b32 s74, 2
	s_waitcnt vmcnt(23)
	s_waitcnt vmcnt(22)
	s_waitcnt vmcnt(21)
	s_waitcnt vmcnt(20)
	s_branch .Lg3_loop

.LBB0_1360:
	v_mov_b64_e32 v[2:3], 0
	v_mov_b64_e32 v[4:5], 0
	v_mov_b64_e32 v[6:7], 0
	v_mov_b64_e32 v[8:9], 0
	v_mov_b64_e32 v[10:11], 0
	v_mov_b64_e32 v[12:13], 0
	v_mov_b64_e32 v[14:15], 0
	v_mov_b64_e32 v[16:17], 0
	v_mov_b64_e32 v[18:19], 0
	v_mov_b64_e32 v[20:21], 0
	v_mov_b64_e32 v[22:23], 0
	v_mov_b64_e32 v[24:25], 0
	v_mov_b64_e32 v[26:27], 0
	v_mov_b64_e32 v[28:29], 0
	v_mov_b64_e32 v[30:31], 0
	v_mov_b64_e32 v[32:33], 0
	v_mov_b64_e32 v[34:35], 0
	v_mov_b64_e32 v[36:37], 0
	v_mov_b64_e32 v[38:39], 0
	v_mov_b64_e32 v[40:41], 0
	v_mov_b64_e32 v[42:43], 0
	v_mov_b64_e32 v[44:45], 0
	v_mov_b64_e32 v[46:47], 0
	v_mov_b64_e32 v[48:49], 0
	v_mov_b64_e32 v[50:51], 0
	v_mov_b64_e32 v[52:53], 0
	v_mov_b64_e32 v[54:55], 0
	v_mov_b64_e32 v[56:57], 0
	v_mov_b64_e32 v[58:59], 0
	v_mov_b64_e32 v[60:61], 0
	v_mov_b64_e32 v[62:63], 0
	v_mov_b64_e32 v[64:65], 0
	v_mov_b64_e32 v[66:67], 0
	v_mov_b64_e32 v[68:69], 0
	v_mov_b64_e32 v[70:71], 0
	v_mov_b64_e32 v[72:73], 0
	v_mov_b64_e32 v[74:75], 0
	v_mov_b64_e32 v[76:77], 0
	v_mov_b64_e32 v[78:79], 0
	v_mov_b64_e32 v[80:81], 0
	v_mov_b64_e32 v[82:83], 0
	v_mov_b64_e32 v[84:85], 0
	v_mov_b64_e32 v[86:87], 0
	v_mov_b64_e32 v[88:89], 0
	v_mov_b64_e32 v[90:91], 0
	v_mov_b64_e32 v[92:93], 0
	v_mov_b64_e32 v[94:95], 0
	v_mov_b64_e32 v[96:97], 0
	v_mov_b64_e32 v[98:99], 0
	v_mov_b64_e32 v[100:101], 0
	v_mov_b64_e32 v[102:103], 0
	v_mov_b64_e32 v[104:105], 0
	v_mov_b64_e32 v[106:107], 0
	v_mov_b64_e32 v[108:109], 0
	v_mov_b64_e32 v[110:111], 0
	v_mov_b64_e32 v[112:113], 0
	v_mov_b64_e32 v[114:115], 0
	v_mov_b64_e32 v[116:117], 0
	v_mov_b64_e32 v[118:119], 0
	v_mov_b64_e32 v[120:121], 0
	v_mov_b64_e32 v[122:123], 0
	v_mov_b64_e32 v[124:125], 0
	v_mov_b64_e32 v[126:127], 0
	v_mov_b64_e32 v[128:129], 0
	s_mov_b32 s39, 0
	s_mov_b32 s52, 2
	s_branch .Lg6_loop

.LBB0_1420:
	v_mov_b64_e32 v[2:3], 0
	v_mov_b64_e32 v[4:5], 0
	v_mov_b64_e32 v[6:7], 0
	v_mov_b64_e32 v[8:9], 0
	v_mov_b64_e32 v[10:11], 0
	v_mov_b64_e32 v[12:13], 0
	v_mov_b64_e32 v[14:15], 0
	v_mov_b64_e32 v[16:17], 0
	v_mov_b64_e32 v[18:19], 0
	v_mov_b64_e32 v[20:21], 0
	v_mov_b64_e32 v[22:23], 0
	v_mov_b64_e32 v[24:25], 0
	v_mov_b64_e32 v[26:27], 0
	v_mov_b64_e32 v[28:29], 0
	v_mov_b64_e32 v[30:31], 0
	v_mov_b64_e32 v[32:33], 0
	v_mov_b64_e32 v[34:35], 0
	v_mov_b64_e32 v[36:37], 0
	v_mov_b64_e32 v[38:39], 0
	v_mov_b64_e32 v[40:41], 0
	v_mov_b64_e32 v[42:43], 0
	v_mov_b64_e32 v[44:45], 0
	v_mov_b64_e32 v[46:47], 0
	v_mov_b64_e32 v[48:49], 0
	v_mov_b64_e32 v[50:51], 0
	v_mov_b64_e32 v[52:53], 0
	v_mov_b64_e32 v[54:55], 0
	v_mov_b64_e32 v[56:57], 0
	v_mov_b64_e32 v[58:59], 0
	v_mov_b64_e32 v[60:61], 0
	v_mov_b64_e32 v[62:63], 0
	v_mov_b64_e32 v[64:65], 0
	v_mov_b64_e32 v[66:67], 0
	v_mov_b64_e32 v[68:69], 0
	v_mov_b64_e32 v[70:71], 0
	v_mov_b64_e32 v[72:73], 0
	v_mov_b64_e32 v[74:75], 0
	v_mov_b64_e32 v[76:77], 0
	v_mov_b64_e32 v[78:79], 0
	v_mov_b64_e32 v[80:81], 0
	v_mov_b64_e32 v[82:83], 0
	v_mov_b64_e32 v[84:85], 0
	v_mov_b64_e32 v[86:87], 0
	v_mov_b64_e32 v[88:89], 0
	v_mov_b64_e32 v[90:91], 0
	v_mov_b64_e32 v[92:93], 0
	v_mov_b64_e32 v[94:95], 0
	v_mov_b64_e32 v[96:97], 0
	v_mov_b64_e32 v[98:99], 0
	v_mov_b64_e32 v[100:101], 0
	v_mov_b64_e32 v[102:103], 0
	v_mov_b64_e32 v[104:105], 0
	v_mov_b64_e32 v[106:107], 0
	v_mov_b64_e32 v[108:109], 0
	v_mov_b64_e32 v[110:111], 0
	v_mov_b64_e32 v[112:113], 0
	v_mov_b64_e32 v[114:115], 0
	v_mov_b64_e32 v[116:117], 0
	v_mov_b64_e32 v[118:119], 0
	v_mov_b64_e32 v[120:121], 0
	v_mov_b64_e32 v[122:123], 0
	v_mov_b64_e32 v[124:125], 0
	v_mov_b64_e32 v[126:127], 0
	v_mov_b64_e32 v[128:129], 0
	s_lshl_b32 s45, s37, 8
	s_mov_b32 s46, 0
	s_mov_b32 s74, 2
	s_branch .Lg7_loop
